# attention softmax max-reduction via v_permlane16/32_swap instead of two ds_bpermute round trips
# speedup vs baseline: 1.0378x; 1.0062x over previous
.LBB0_279:
	v_max_f32_e32 v138, v113, v113
	v_max_f32_e32 v139, v112, v112
	v_max_f32_e32 v138, v139, v138
	v_max3_f32 v138, v138, v114, v115
	v_max3_f32 v138, v138, v116, v117
	v_max3_f32 v138, v138, v118, v119
	v_max3_f32 v138, v138, v120, v121
	v_max3_f32 v138, v138, v122, v123
	v_max3_f32 v138, v138, v124, v125
	v_max3_f32 v138, v138, v126, v127
	v_mov_b32_e32 v139, v138
	s_nop 1
	v_permlane16_swap_b32 v138, v139
	s_nop 0
	v_max_f32_e32 v138, v138, v139
	v_mov_b32_e32 v139, v138
	s_nop 1
	v_permlane32_swap_b32 v138, v139
	s_nop 0
	v_max3_f32 v219, v128, v138, v139
	v_sub_f32_e32 v128, v128, v219
	v_exp_f32_e32 v128, v128
	s_nop 0
	v_cmp_neq_f32_e32 vcc, 1.0, v128
	s_cbranch_vccz .LBB0_281
	v_pk_mul_f32 v[62:63], v[62:63], v[128:129] op_sel_hi:[1,0]
	v_pk_mul_f32 v[60:61], v[60:61], v[128:129] op_sel_hi:[1,0]
	v_pk_mul_f32 v[58:59], v[58:59], v[128:129] op_sel_hi:[1,0]
	v_pk_mul_f32 v[56:57], v[56:57], v[128:129] op_sel_hi:[1,0]
	v_pk_mul_f32 v[54:55], v[54:55], v[128:129] op_sel_hi:[1,0]
	v_pk_mul_f32 v[52:53], v[52:53], v[128:129] op_sel_hi:[1,0]
	v_pk_mul_f32 v[50:51], v[50:51], v[128:129] op_sel_hi:[1,0]
	v_pk_mul_f32 v[48:49], v[48:49], v[128:129] op_sel_hi:[1,0]
	v_pk_mul_f32 v[46:47], v[46:47], v[128:129] op_sel_hi:[1,0]
	v_pk_mul_f32 v[44:45], v[44:45], v[128:129] op_sel_hi:[1,0]
	v_pk_mul_f32 v[42:43], v[42:43], v[128:129] op_sel_hi:[1,0]
	v_pk_mul_f32 v[40:41], v[40:41], v[128:129] op_sel_hi:[1,0]
	v_pk_mul_f32 v[38:39], v[38:39], v[128:129] op_sel_hi:[1,0]
	v_pk_mul_f32 v[36:37], v[36:37], v[128:129] op_sel_hi:[1,0]
	v_pk_mul_f32 v[34:35], v[34:35], v[128:129] op_sel_hi:[1,0]
	v_pk_mul_f32 v[32:33], v[32:33], v[128:129] op_sel_hi:[1,0]

.LBB0_283:
	v_max_f32_e32 v120, v97, v97
	v_max_f32_e32 v138, v96, v96
	v_max_f32_e32 v120, v138, v120
	v_max3_f32 v120, v120, v98, v99
	v_max3_f32 v120, v120, v100, v101
	v_max3_f32 v120, v120, v102, v103
	v_max3_f32 v120, v120, v104, v105
	v_max3_f32 v120, v120, v106, v107
	v_max3_f32 v120, v120, v108, v109
	v_max3_f32 v120, v120, v110, v111
	v_mov_b32_e32 v138, v120
	s_nop 1
	v_permlane16_swap_b32 v120, v138
	s_nop 0
	v_max_f32_e32 v120, v120, v138
	v_mov_b32_e32 v138, v120
	s_nop 1
	v_permlane32_swap_b32 v120, v138
	s_nop 0
	v_max3_f32 v230, v220, v120, v138
	v_sub_f32_e32 v120, v220, v230
	v_exp_f32_e32 v120, v120
	s_nop 0
	v_cmp_neq_f32_e32 vcc, 1.0, v120
	s_cbranch_vccz .LBB0_285
	v_pk_mul_f32 v[30:31], v[30:31], v[120:121] op_sel_hi:[1,0]
	v_pk_mul_f32 v[28:29], v[28:29], v[120:121] op_sel_hi:[1,0]
	v_pk_mul_f32 v[22:23], v[22:23], v[120:121] op_sel_hi:[1,0]
	v_pk_mul_f32 v[20:21], v[20:21], v[120:121] op_sel_hi:[1,0]
	v_pk_mul_f32 v[26:27], v[26:27], v[120:121] op_sel_hi:[1,0]
	v_pk_mul_f32 v[24:25], v[24:25], v[120:121] op_sel_hi:[1,0]
	v_pk_mul_f32 v[18:19], v[18:19], v[120:121] op_sel_hi:[1,0]
	v_pk_mul_f32 v[16:17], v[16:17], v[120:121] op_sel_hi:[1,0]
	v_pk_mul_f32 v[14:15], v[14:15], v[120:121] op_sel_hi:[1,0]
	v_pk_mul_f32 v[12:13], v[12:13], v[120:121] op_sel_hi:[1,0]
	v_pk_mul_f32 v[10:11], v[10:11], v[120:121] op_sel_hi:[1,0]
	v_pk_mul_f32 v[8:9], v[8:9], v[120:121] op_sel_hi:[1,0]
	v_pk_mul_f32 v[6:7], v[6:7], v[120:121] op_sel_hi:[1,0]
	v_pk_mul_f32 v[4:5], v[4:5], v[120:121] op_sel_hi:[1,0]
	v_pk_mul_f32 v[2:3], v[2:3], v[120:121] op_sel_hi:[1,0]
	v_pk_mul_f32 v[0:1], v[0:1], v[120:121] op_sel_hi:[1,0]
